# diff-attention loop: causal-mask index VALU moved into the diagonal-only blocks, score accumulators start from inline 0 (no per-tile 16-register init)
# speedup vs baseline: 1.0135x; 1.0135x over previous
.LBB0_1749:
	s_sub_i32 s0, s14, 63
	v_cmp_le_i32_e32 vcc, s0, v174
	s_and_saveexec_b64 s[6:7], vcc
	s_cbranch_execz .LBB0_1746
	v_add_u32_e32 v66, s15, v186
	v_add_u32_e32 v163, v66, v0
	ds_read_b128 v[82:85], v163
	ds_read_b128 v[86:89], v163 offset:4608
	ds_read_b128 v[90:93], v163 offset:32
	ds_read_b128 v[94:97], v163 offset:4640
	ds_read_b128 v[212:215], v163 offset:64
	ds_read_b128 v[220:223], v163 offset:4672
	ds_read_b128 v[240:243], v163 offset:96
	ds_read_b128 v[244:247], v163 offset:4704
	s_mov_b32 s69, s68
	s_mov_b32 s70, s68
	s_mov_b32 s71, s68
	s_mov_b32 s72, s68
	s_mov_b32 s73, s68
	s_mov_b32 s74, s68
	s_mov_b32 s75, s68
	s_mov_b32 s76, s68
	s_mov_b32 s77, s68
	s_mov_b32 s78, s68
	s_mov_b32 s79, s68
	s_mov_b32 s80, s68
	s_mov_b32 s81, s68
	s_mov_b32 s82, s68
	s_mov_b32 s83, s68
	v_cmp_gt_i32_e32 vcc, s14, v172
	s_waitcnt lgkmcnt(7)
	v_mfma_f32_32x32x16_bf16 v[114:129], v[82:85], v[130:133], 0
	s_waitcnt lgkmcnt(6)
	v_mfma_f32_32x32x16_bf16 v[98:113], v[86:89], v[130:133], 0
	s_waitcnt lgkmcnt(5)
	v_mfma_f32_32x32x16_bf16 v[114:129], v[90:93], v[134:137], v[114:129]
	s_waitcnt lgkmcnt(4)
	v_mfma_f32_32x32x16_bf16 v[98:113], v[94:97], v[134:137], v[98:113]
	s_and_saveexec_b64 s[8:9], vcc
	s_cbranch_execz .LBB0_1752
	v_add_u32_e32 v70, s14, v157
	v_subrev_u32_e32 v205, 63, v70
	v_subrev_u32_e32 v211, 31, v70
	v_subrev_u32_e32 v210, 30, v70
	v_subrev_u32_e32 v209, 61, v70
	v_subrev_u32_e32 v208, 29, v70
	v_subrev_u32_e32 v207, 60, v70
	v_subrev_u32_e32 v206, 28, v70
	v_subrev_u32_e32 v204, 55, v70
	v_subrev_u32_e32 v203, 23, v70
	v_subrev_u32_e32 v202, 54, v70
	v_subrev_u32_e32 v201, 22, v70
	v_subrev_u32_e32 v200, 53, v70
	v_subrev_u32_e32 v199, 21, v70
	v_subrev_u32_e32 v198, 52, v70
	v_subrev_u32_e32 v197, 20, v70
	v_subrev_u32_e32 v196, 47, v70
	v_add_u32_e32 v195, -15, v70
	v_subrev_u32_e32 v194, 46, v70
	v_add_u32_e32 v193, -14, v70
	v_subrev_u32_e32 v192, 45, v70
	v_add_u32_e32 v191, -13, v70
	v_subrev_u32_e32 v190, 44, v70
	v_add_u32_e32 v171, -12, v70
	v_subrev_u32_e32 v170, 39, v70
	v_add_u32_e32 v169, -7, v70
	v_subrev_u32_e32 v168, 38, v70
	v_add_u32_e32 v167, -6, v70
	v_subrev_u32_e32 v166, 37, v70
	v_add_u32_e32 v165, -5, v70
	v_subrev_u32_e32 v164, 36, v70
	v_add_u32_e32 v162, -4, v70
	v_cmp_le_i32_e64 s[0:1], v211, v156
	s_nop 1
	v_cndmask_b32_e64 v98, v236, v98, s[0:1]
	v_cmp_lt_i32_e64 s[0:1], v205, v156
	s_nop 1
	v_cndmask_b32_e64 v115, v236, v115, s[0:1]
	v_cmp_le_i32_e64 s[0:1], v205, v156
	s_nop 1
	v_cndmask_b32_e64 v114, v236, v114, s[0:1]
	v_cmp_le_i32_e64 s[0:1], v210, v156
	s_nop 1
	v_cndmask_b32_e64 v99, v236, v99, s[0:1]
	v_cmp_le_i32_e64 s[0:1], v209, v156
	s_nop 1
	v_cndmask_b32_e64 v116, v236, v116, s[0:1]
	v_cmp_le_i32_e64 s[0:1], v208, v156
	s_nop 1
	v_cndmask_b32_e64 v100, v236, v100, s[0:1]
	v_cmp_le_i32_e64 s[0:1], v207, v156
	s_nop 1
	v_cndmask_b32_e64 v117, v236, v117, s[0:1]
	v_cmp_le_i32_e64 s[0:1], v206, v156
	s_nop 1
	v_cndmask_b32_e64 v101, v236, v101, s[0:1]
	v_cmp_le_i32_e64 s[0:1], v204, v156
	s_nop 1
	v_cndmask_b32_e64 v118, v236, v118, s[0:1]
	v_cmp_le_i32_e64 s[0:1], v203, v156
	s_nop 1
	v_cndmask_b32_e64 v102, v236, v102, s[0:1]
	v_cmp_le_i32_e64 s[0:1], v202, v156
	s_nop 1
	v_cndmask_b32_e64 v119, v236, v119, s[0:1]
	v_cmp_le_i32_e64 s[0:1], v201, v156
	s_nop 1
	v_cndmask_b32_e64 v103, v236, v103, s[0:1]
	v_cmp_le_i32_e64 s[0:1], v200, v156
	s_nop 1
	v_cndmask_b32_e64 v120, v236, v120, s[0:1]
	v_cmp_le_i32_e64 s[0:1], v199, v156
	s_nop 1
	v_cndmask_b32_e64 v104, v236, v104, s[0:1]
	v_cmp_le_i32_e64 s[0:1], v198, v156
	s_nop 1
	v_cndmask_b32_e64 v121, v236, v121, s[0:1]
	v_cmp_le_i32_e64 s[0:1], v197, v156
	s_nop 1
	v_cndmask_b32_e64 v105, v236, v105, s[0:1]
	v_cmp_le_i32_e64 s[0:1], v196, v156
	s_nop 1
	v_cndmask_b32_e64 v122, v236, v122, s[0:1]
	v_cmp_le_i32_e64 s[0:1], v195, v156
	s_nop 1
	v_cndmask_b32_e64 v106, v236, v106, s[0:1]
	v_cmp_le_i32_e64 s[0:1], v194, v156
	s_nop 1
	v_cndmask_b32_e64 v123, v236, v123, s[0:1]
	v_cmp_le_i32_e64 s[0:1], v193, v156
	s_nop 1
	v_cndmask_b32_e64 v107, v236, v107, s[0:1]
	v_cmp_le_i32_e64 s[0:1], v192, v156
	s_nop 1
	v_cndmask_b32_e64 v124, v236, v124, s[0:1]
	v_cmp_le_i32_e64 s[0:1], v191, v156
	s_nop 1
	v_cndmask_b32_e64 v108, v236, v108, s[0:1]
	v_cmp_le_i32_e64 s[0:1], v190, v156
	s_nop 1
	v_cndmask_b32_e64 v125, v236, v125, s[0:1]
	v_cmp_le_i32_e64 s[0:1], v171, v156
	s_nop 1
	v_cndmask_b32_e64 v109, v236, v109, s[0:1]
	v_cmp_le_i32_e64 s[0:1], v170, v156
	s_nop 1
	v_cndmask_b32_e64 v126, v236, v126, s[0:1]
	v_cmp_le_i32_e64 s[0:1], v169, v156
	s_nop 1
	v_cndmask_b32_e64 v110, v236, v110, s[0:1]
	v_cmp_le_i32_e64 s[0:1], v168, v156
	s_nop 1
	v_cndmask_b32_e64 v127, v236, v127, s[0:1]
	v_cmp_le_i32_e64 s[0:1], v167, v156
	s_nop 1
	v_cndmask_b32_e64 v111, v236, v111, s[0:1]
	v_cmp_le_i32_e64 s[0:1], v166, v156
	s_nop 1
	v_cndmask_b32_e64 v128, v236, v128, s[0:1]
	v_cmp_le_i32_e64 s[0:1], v165, v156
	s_nop 1
	v_cndmask_b32_e64 v112, v236, v112, s[0:1]
	v_cmp_le_i32_e64 s[0:1], v164, v156
	s_nop 1
	v_cndmask_b32_e64 v129, v236, v129, s[0:1]
	v_cmp_le_i32_e64 s[0:1], v162, v156
	s_nop 1
	v_cndmask_b32_e64 v113, v236, v113, s[0:1]
.LBB0_1752:
	s_or_b64 exec, exec, s[8:9]
	s_waitcnt lgkmcnt(3)
	v_mfma_f32_32x32x16_bf16 v[82:97], v[212:215], v[138:141], 0
	s_waitcnt lgkmcnt(2)
	v_mfma_f32_32x32x16_bf16 v[66:81], v[220:223], v[138:141], 0
	s_waitcnt lgkmcnt(1)
	v_mfma_f32_32x32x16_bf16 v[82:97], v[240:243], v[142:145], v[82:97]
	s_waitcnt lgkmcnt(0)
	v_mfma_f32_32x32x16_bf16 v[66:81], v[244:247], v[142:145], v[66:81]
	s_and_saveexec_b64 s[0:1], vcc
	s_cbranch_execz .LBB0_1745
	v_cmp_le_i32_e32 vcc, v211, v156
	s_nop 8
	v_cndmask_b32_e32 v66, v236, v66, vcc
	v_cmp_lt_i32_e32 vcc, v205, v156
	s_nop 1
	v_cndmask_b32_e32 v83, v236, v83, vcc
	v_cmp_le_i32_e32 vcc, v205, v156
	s_nop 1
	v_cndmask_b32_e32 v82, v236, v82, vcc
	v_cmp_le_i32_e32 vcc, v210, v156
	s_nop 1
	v_cndmask_b32_e32 v67, v236, v67, vcc
	v_cmp_le_i32_e32 vcc, v209, v156
	s_nop 1
	v_cndmask_b32_e32 v84, v236, v84, vcc
	v_cmp_le_i32_e32 vcc, v208, v156
	s_nop 1
	v_cndmask_b32_e32 v68, v236, v68, vcc
	v_cmp_le_i32_e32 vcc, v207, v156
	s_nop 1
	v_cndmask_b32_e32 v85, v236, v85, vcc
	v_cmp_le_i32_e32 vcc, v206, v156
	s_nop 1
	v_cndmask_b32_e32 v69, v236, v69, vcc
	v_cmp_le_i32_e32 vcc, v204, v156
	s_nop 1
	v_cndmask_b32_e32 v86, v236, v86, vcc
	v_cmp_le_i32_e32 vcc, v203, v156
	s_nop 1
	v_cndmask_b32_e32 v70, v236, v70, vcc
	v_cmp_le_i32_e32 vcc, v202, v156
	s_nop 1
	v_cndmask_b32_e32 v87, v236, v87, vcc
	v_cmp_le_i32_e32 vcc, v201, v156
	s_nop 1
	v_cndmask_b32_e32 v71, v236, v71, vcc
	v_cmp_le_i32_e32 vcc, v200, v156
	s_nop 1
	v_cndmask_b32_e32 v88, v236, v88, vcc
	v_cmp_le_i32_e32 vcc, v199, v156
	s_nop 1
	v_cndmask_b32_e32 v72, v236, v72, vcc
	v_cmp_le_i32_e32 vcc, v198, v156
	s_nop 1
	v_cndmask_b32_e32 v89, v236, v89, vcc
	v_cmp_le_i32_e32 vcc, v197, v156
	s_nop 1
	v_cndmask_b32_e32 v73, v236, v73, vcc
	v_cmp_le_i32_e32 vcc, v196, v156
	s_nop 1
	v_cndmask_b32_e32 v90, v236, v90, vcc
	v_cmp_le_i32_e32 vcc, v195, v156
	s_nop 1
	v_cndmask_b32_e32 v74, v236, v74, vcc
	v_cmp_le_i32_e32 vcc, v194, v156
	s_nop 1
	v_cndmask_b32_e32 v91, v236, v91, vcc
	v_cmp_le_i32_e32 vcc, v193, v156
	s_nop 1
	v_cndmask_b32_e32 v75, v236, v75, vcc
	v_cmp_le_i32_e32 vcc, v192, v156
	s_nop 1
	v_cndmask_b32_e32 v92, v236, v92, vcc
	v_cmp_le_i32_e32 vcc, v191, v156
	s_nop 1
	v_cndmask_b32_e32 v76, v236, v76, vcc
	v_cmp_le_i32_e32 vcc, v190, v156
	s_nop 1
	v_cndmask_b32_e32 v93, v236, v93, vcc
	v_cmp_le_i32_e32 vcc, v171, v156
	s_nop 1
	v_cndmask_b32_e32 v77, v236, v77, vcc
	v_cmp_le_i32_e32 vcc, v170, v156
	s_nop 1
	v_cndmask_b32_e32 v94, v236, v94, vcc
	v_cmp_le_i32_e32 vcc, v169, v156
	s_nop 1
	v_cndmask_b32_e32 v78, v236, v78, vcc
	v_cmp_le_i32_e32 vcc, v168, v156
	s_nop 1
	v_cndmask_b32_e32 v95, v236, v95, vcc
	v_cmp_le_i32_e32 vcc, v167, v156
	s_nop 1
	v_cndmask_b32_e32 v79, v236, v79, vcc
	v_cmp_le_i32_e32 vcc, v166, v156
	s_nop 1
	v_cndmask_b32_e32 v96, v236, v96, vcc
	v_cmp_le_i32_e32 vcc, v165, v156
	s_nop 1
	v_cndmask_b32_e32 v80, v236, v80, vcc
	v_cmp_le_i32_e32 vcc, v164, v156
	s_nop 1
	v_cndmask_b32_e32 v97, v236, v97, vcc
	v_cmp_le_i32_e32 vcc, v162, v156
	s_nop 1
	v_cndmask_b32_e32 v81, v236, v81, vcc
	s_branch .LBB0_1745
